# delta recurrence producer: mid-iteration vmcnt waits that forced the previous stores' acknowledgement removed (drain once before the loop)
# baseline (speedup 1.0000x reference)
; #define LAS __attribute__((address_space(3)))
; __device__ __forceinline__ unsigned f2bf(float f) { return pk2(f, f) & 0xffffu; }
; __device__ __forceinline__ void unpack8(const u32x4 u, float* x) { x[0] = bflo(u.x); x[1] = bfhi(u.x); x[2] = bflo(u.y); x[3] = bfhi(u.y); x[4] = bflo(u.z); x[5] = bfhi(u.z); x[6] = bflo(u.w); x[7] = bfhi(u.w); }
; __device__ __forceinline__ int perm16(int e) { return (e & ~12) | ((e >> 1) & 4) | ((e << 1) & 8); }
; __device__ __forceinline__ void delta_rec_stage(LAS unsigned char* buf, int pt, const DeltaPre& dp) {
;     const int tt = pt >> 3, dg = pt & 7, d0 = dg * 16;
;     { LAS bf16* dst = (LAS bf16*)(buf + (pt < 128 ? DR_TI : DR_AT)) + ((pt & 127) >> 2) * 40 + (pt & 3) * 8; *(LAS u32x4*)dst = dp.tia; }
;     if (pt == 0) *(LAS float*)(buf + DR_EGL) = __expf(dp.gl);
;     const float eg = __expf(dp.gct), ekd = __expf(dp.gl - dp.gct);
;     const float fq = dp.nq * eg, fkb = dp.nk * dp.bet * eg, fkd = dp.nk * ekd, bet = dp.bet;
;     float k[16], q[16], v[16];
;     unpack8(dp.k0, k); unpack8(dp.k1, k + 8); unpack8(dp.q0, q); unpack8(dp.q1, q + 8); unpack8(dp.v0, v); unpack8(dp.v1, v + 8);
;     LAS bf16* KB = (LAS bf16*)(buf + DR_KB) + tt * 136 + d0; LAS bf16* QD = (LAS bf16*)(buf + DR_QD) + tt * 136 + d0;
;     *(LAS bf16x8*)KB = pack8(k[0] * fkb, k[1] * fkb, k[2] * fkb, k[3] * fkb, k[8] * fkb, k[9] * fkb, k[10] * fkb, k[11] * fkb);
;     *(LAS bf16x8*)(KB + 8) = pack8(k[4] * fkb, k[5] * fkb, k[6] * fkb, k[7] * fkb, k[12] * fkb, k[13] * fkb, k[14] * fkb, k[15] * fkb);
;     *(LAS bf16x8*)QD = pack8(q[0] * fq, q[1] * fq, q[2] * fq, q[3] * fq, q[8] * fq, q[9] * fq, q[10] * fq, q[11] * fq);
;     *(LAS bf16x8*)(QD + 8) = pack8(q[4] * fq, q[5] * fq, q[6] * fq, q[7] * fq, q[12] * fq, q[13] * fq, q[14] * fq, q[15] * fq);
;     LAS bf16* KDT = (LAS bf16*)(buf + DR_KDT) + d0 * 40 + perm16(tt);
; #pragma unroll
;     for (int e = 0; e < 16; ++e) KDT[e * 40] = (bf16)f2bf(k[e] * fkd);
;     LAS float* VB = (LAS float*)(buf + DR_VB) + tt * 132 + d0;
; #pragma unroll
;     for (int e4 = 0; e4 < 4; ++e4) *(LAS f32x4*)(VB + 4 * e4) = (f32x4){v[4 * e4] * bet, v[4 * e4 + 1] * bet, v[4 * e4 + 2] * bet, v[4 * e4 + 3] * bet};
; }
.LBB0_1837:
	s_or_b64 exec, exec, s[18:19]
	v_lshrrev_b32_e32 v33, 1, v22
	v_and_b32_e32 v128, 4, v33
	v_lshlrev_b32_e32 v33, 1, v22
	v_and_b32_e32 v129, 8, v33
	v_mul_f32_e32 v33, 0x3fb8aa3b, v117
	v_sub_f32_e32 v34, v118, v117
	v_exp_f32_e32 v33, v33
	v_mul_f32_e32 v34, 0x3fb8aa3b, v34
	v_exp_f32_e32 v34, v34
	s_movk_i32 s18, 0x88
	v_mul_f32_e32 v35, v119, v110
	v_mul_lo_u32 v32, v22, s18
	v_mul_f32_e32 v42, v35, v33
	v_lshlrev_b32_e32 v52, 16, v84
	v_and_b32_e32 v53, 0xffff0000, v84
	v_lshlrev_b32_e32 v54, 16, v85
	v_and_b32_e32 v55, 0xffff0000, v85
	v_lshlrev_b32_e32 v56, 16, v80
	v_and_b32_e32 v57, 0xffff0000, v80
	v_lshlrev_b32_e32 v60, 16, v81
	v_and_b32_e32 v61, 0xffff0000, v81
	v_mul_f32_e32 v40, v120, v33
	v_mul_f32_e32 v117, v119, v34
	v_lshlrev_b32_e32 v91, 1, v32
	v_pk_mul_f32 v[32:33], v[42:43], v[52:53] op_sel_hi:[0,1]
	v_pk_mul_f32 v[34:35], v[42:43], v[54:55] op_sel_hi:[0,1]
	v_pk_mul_f32 v[58:59], v[42:43], v[56:57] op_sel_hi:[0,1]
	v_pk_mul_f32 v[62:63], v[42:43], v[60:61] op_sel_hi:[0,1]
	v_add3_u32 v118, 0, v91, v114
	v_cvt_pk_bf16_f32 v32, v32, v33
	v_cvt_pk_bf16_f32 v33, v34, v35
	v_cvt_pk_bf16_f32 v34, v58, v59
	v_cvt_pk_bf16_f32 v35, v62, v63
	v_lshlrev_b32_e32 v58, 16, v86
	v_and_b32_e32 v59, 0xffff0000, v86
	v_lshlrev_b32_e32 v62, 16, v87
	v_and_b32_e32 v63, 0xffff0000, v87
	v_lshlrev_b32_e32 v84, 16, v82
	v_and_b32_e32 v85, 0xffff0000, v82
	v_lshlrev_b32_e32 v86, 16, v83
	v_and_b32_e32 v87, 0xffff0000, v83
	ds_write_b128 v118, v[32:35] offset:49680
	v_pk_mul_f32 v[32:33], v[42:43], v[58:59] op_sel_hi:[0,1]
	v_pk_mul_f32 v[34:35], v[42:43], v[62:63] op_sel_hi:[0,1]
	v_pk_mul_f32 v[80:81], v[42:43], v[84:85] op_sel_hi:[0,1]
	v_pk_mul_f32 v[42:43], v[42:43], v[86:87] op_sel_hi:[0,1]
	v_cvt_pk_bf16_f32 v32, v32, v33
	v_cvt_pk_bf16_f32 v33, v34, v35
	v_cvt_pk_bf16_f32 v34, v80, v81
	v_cvt_pk_bf16_f32 v35, v42, v43
	ds_write_b128 v118, v[32:35] offset:49696
	v_lshlrev_b32_e32 v32, 16, v76
	v_and_b32_e32 v33, 0xffff0000, v76
	v_lshlrev_b32_e32 v34, 16, v77
	v_and_b32_e32 v35, 0xffff0000, v77
	v_lshlrev_b32_e32 v42, 16, v72
	v_and_b32_e32 v43, 0xffff0000, v72
	v_lshlrev_b32_e32 v72, 16, v73
	v_and_b32_e32 v73, 0xffff0000, v73
	v_pk_mul_f32 v[32:33], v[40:41], v[32:33] op_sel_hi:[0,1]
	v_pk_mul_f32 v[34:35], v[40:41], v[34:35] op_sel_hi:[0,1]
	v_pk_mul_f32 v[42:43], v[40:41], v[42:43] op_sel_hi:[0,1]
	v_pk_mul_f32 v[72:73], v[40:41], v[72:73] op_sel_hi:[0,1]
	v_cvt_pk_bf16_f32 v32, v32, v33
	v_cvt_pk_bf16_f32 v33, v34, v35
	v_cvt_pk_bf16_f32 v34, v42, v43
	v_cvt_pk_bf16_f32 v35, v72, v73
	s_movk_i32 s18, 0x210
	ds_write_b128 v118, v[32:35] offset:58384
	v_lshlrev_b32_e32 v32, 16, v78
	v_and_b32_e32 v33, 0xffff0000, v78
	v_lshlrev_b32_e32 v34, 16, v79
	v_and_b32_e32 v35, 0xffff0000, v79
	v_lshlrev_b32_e32 v42, 16, v74
	v_and_b32_e32 v43, 0xffff0000, v74
	v_lshlrev_b32_e32 v72, 16, v75
	v_and_b32_e32 v73, 0xffff0000, v75
	v_mul_lo_u32 v88, v22, s18
	s_add_i32 s18, 0, 0x18420
	v_pk_mul_f32 v[32:33], v[40:41], v[32:33] op_sel_hi:[0,1]
	v_pk_mul_f32 v[34:35], v[40:41], v[34:35] op_sel_hi:[0,1]
	v_pk_mul_f32 v[42:43], v[40:41], v[42:43] op_sel_hi:[0,1]
	v_pk_mul_f32 v[40:41], v[40:41], v[72:73] op_sel_hi:[0,1]
	v_mul_u32_u24_e32 v90, 0x50, v27
	v_bfe_u32 v230, v167, 3, 1
	s_mov_b32 s42, 0xfdfe0606
	v_mul_lo_u32 v231, v230, s42
	v_add_u32_e32 v231, 0x5040100, v231
	v_mul_u32_u24_e32 v230, 0x4e, v230
	v_and_b32_e32 v127, -13, v22
	v_add3_u32 v89, s18, v88, v111
	v_cvt_pk_bf16_f32 v32, v32, v33
	v_cvt_pk_bf16_f32 v33, v34, v35
	v_cvt_pk_bf16_f32 v34, v42, v43
	v_cvt_pk_bf16_f32 v35, v40, v41
	s_add_i32 s18, 0, 0x10610
	v_lshlrev_b32_e32 v80, 1, v128
	ds_write_b128 v118, v[32:35] offset:58400
	v_add3_u32 v32, s18, v90, v80
	v_lshlrev_b32_e32 v81, 1, v127
	v_lshlrev_b32_e32 v82, 1, v129
	v_mul_f32_e32 v33, v117, v52
	v_add3_u32 v32, v32, v81, v82
	v_cvt_pk_bf16_f32 v33, v33, s0
	ds_write_b16 v32, v33
	v_mul_f32_e32 v33, v117, v53
	v_cvt_pk_bf16_f32 v33, v33, s0
	ds_write_b16 v32, v33 offset:80
	v_mul_f32_e32 v33, v117, v54
	v_cvt_pk_bf16_f32 v33, v33, s0
	ds_write_b16 v32, v33 offset:160
	v_mul_f32_e32 v33, v117, v55
	v_cvt_pk_bf16_f32 v33, v33, s0
	ds_write_b16 v32, v33 offset:240
	v_mul_f32_e32 v33, v117, v58
	v_cvt_pk_bf16_f32 v33, v33, s0
	ds_write_b16 v32, v33 offset:320
	v_mul_f32_e32 v33, v117, v59
	v_cvt_pk_bf16_f32 v33, v33, s0
	ds_write_b16 v32, v33 offset:400
	v_mul_f32_e32 v33, v117, v62
	v_cvt_pk_bf16_f32 v33, v33, s0
	ds_write_b16 v32, v33 offset:480
	v_mul_f32_e32 v33, v117, v63
	v_cvt_pk_bf16_f32 v33, v33, s0
	ds_write_b16 v32, v33 offset:560
	v_mul_f32_e32 v33, v117, v56
	v_cvt_pk_bf16_f32 v33, v33, s0
	ds_write_b16 v32, v33 offset:640
	v_mul_f32_e32 v33, v117, v57
	v_cvt_pk_bf16_f32 v33, v33, s0
	ds_write_b16 v32, v33 offset:720
	v_mul_f32_e32 v33, v117, v60
	v_cvt_pk_bf16_f32 v33, v33, s0
	ds_write_b16 v32, v33 offset:800
	v_mul_f32_e32 v33, v117, v61
	v_cvt_pk_bf16_f32 v33, v33, s0
	ds_write_b16 v32, v33 offset:880
	v_mul_f32_e32 v33, v117, v84
	v_cvt_pk_bf16_f32 v33, v33, s0
	ds_write_b16 v32, v33 offset:960
	v_mul_f32_e32 v33, v117, v85
	v_cvt_pk_bf16_f32 v33, v33, s0
	ds_write_b16 v32, v33 offset:1040
	v_mul_f32_e32 v33, v117, v86
	v_cvt_pk_bf16_f32 v33, v33, s0
	ds_write_b16 v32, v33 offset:1120
	v_mul_f32_e32 v33, v117, v87
	v_cvt_pk_bf16_f32 v33, v33, s0
	ds_write_b16 v32, v33 offset:1200
	s_add_i32 s18, 0, 0x14210
	v_lshlrev_b32_e32 v32, 16, v68
	v_and_b32_e32 v33, 0xffff0000, v68
	v_lshlrev_b32_e32 v34, 16, v69
	v_and_b32_e32 v35, 0xffff0000, v69
	v_add3_u32 v40, s18, v88, v111
	v_pk_mul_f32 v[32:33], v[110:111], v[32:33] op_sel_hi:[0,1]
	v_pk_mul_f32 v[34:35], v[110:111], v[34:35] op_sel_hi:[0,1]
	ds_write_b128 v40, v[32:35]
	v_lshlrev_b32_e32 v32, 16, v70
	v_and_b32_e32 v33, 0xffff0000, v70
	v_lshlrev_b32_e32 v34, 16, v71
	v_and_b32_e32 v35, 0xffff0000, v71
	v_pk_mul_f32 v[32:33], v[110:111], v[32:33] op_sel_hi:[0,1]
	v_pk_mul_f32 v[34:35], v[110:111], v[34:35] op_sel_hi:[0,1]
	ds_write_b128 v40, v[32:35] offset:16
	v_lshlrev_b32_e32 v32, 16, v64
	v_and_b32_e32 v33, 0xffff0000, v64
	v_lshlrev_b32_e32 v34, 16, v65
	v_and_b32_e32 v35, 0xffff0000, v65
	v_pk_mul_f32 v[32:33], v[110:111], v[32:33] op_sel_hi:[0,1]
	v_pk_mul_f32 v[34:35], v[110:111], v[34:35] op_sel_hi:[0,1]
	ds_write_b128 v40, v[32:35] offset:32
	v_lshlrev_b32_e32 v32, 16, v66
	v_and_b32_e32 v33, 0xffff0000, v66
	v_lshlrev_b32_e32 v34, 16, v67
	v_and_b32_e32 v35, 0xffff0000, v67
	v_pk_mul_f32 v[32:33], v[110:111], v[32:33] op_sel_hi:[0,1]
	v_pk_mul_f32 v[34:35], v[110:111], v[34:35] op_sel_hi:[0,1]
	ds_write_b128 v40, v[32:35] offset:48
	v_lshl_add_u64 v[32:33], v[20:21], 0, s[12:13]
	v_and_b32_e32 v20, 0x7f, v26
	v_lshlrev_b32_e32 v20, 4, v20
	v_lshl_add_u64 v[32:33], v[32:33], 0, v[20:21]
	v_lshl_add_u64 v[24:25], s[4:5], 0, v[24:25]
	v_add_lshl_u32 v20, s20, v27, 1
	v_lshl_add_u64 v[72:73], v[24:25], 0, v[20:21]
	v_and_b32_e32 v20, 7, v26
	s_waitcnt lgkmcnt(0)
	s_barrier
; __device__ __forceinline__ int opq(int x) { asm volatile("" : "+v"(x)); return x; }
; __device__ __forceinline__ unsigned char* karg_ws() { return *(volatile KAS ucptr_t*)((const KAS char*)__builtin_amdgcn_kernarg_segment_ptr() + 264); }
; #define INP(k) karg_in(k)
; #define tid opq((wave << 6) | lane_now())
; __device__ __forceinline__ void delta_rec_task(const Params& P, LAS unsigned char* lds, int b, int h, int tid) {
;     ...
;     if (producer) {
;         const int pt = opq(tid) - 256;
;         float dn16[16];
; #pragma unroll
;         for (int e = 0; e < 16; ++e) dn16[e] = INP(25)[(pt & 7) * 16 + e];
;         bf16* zgp = (bf16*)(karg_ws() + WS_Z + 5 * ZB) + ((size_t)b * SEQ + (pt >> 3)) * D + h * 128 + (pt & 7) * 16;
;         u32x4 zc0 = {0u, 0u, 0u, 0u}, zc1 = zc0, zn0, zn1;
;     ...
;         for (int c = 0; c < NC; ++c) {
;             if (c > 0) { dcur = dnxt; zc0 = zn0; zc1 = zn1; }
;             if (c + 2 < NC) delta_pre_load(b, h, c + 2, pt, dnxt);
;             zn0 = *(const u32x4*)(zgp + (size_t)c * 32 * D); zn1 = *(const u32x4*)(zgp + (size_t)c * 32 * D + 8);
	v_lshlrev_b64 v[74:75], 2, v[22:23]
	v_lshl_add_u64 v[22:23], v[24:25], 0, s[14:15]
	v_lshlrev_b32_e32 v20, 5, v20
	s_mov_b64 s[12:13], 0x1800
	v_lshl_add_u64 v[20:21], v[22:23], 0, v[20:21]
	v_lshl_add_u64 v[70:71], v[32:33], 0, s[12:13]
	s_lshl_b64 s[4:5], s[2:3], 13
	v_lshl_add_u64 v[76:77], s[16:17], 0, v[20:21]
	s_mov_b64 s[12:13], 0
	s_mov_b64 s[16:17], 0xb130000
	s_mov_b64 s[18:19], 0x3030000
	s_mov_b64 s[20:21], 0xd170000
	s_mov_b32 s3, 0xb130000
	s_mov_b32 s14, 0x3030000
	s_mov_b32 s34, 0xd170000
	s_mov_b32 s35, 0x2880000
	v_mov_b32_e32 v69, 0x2880000
	s_mov_b64 s[22:23], 0xf190000
	v_mov_b32_e32 v83, 0x358637bd
	s_mov_b64 s[24:25], 0x800
	s_mov_b32 s36, s15
	s_waitcnt vmcnt(0)

; #define LAS __attribute__((address_space(3)))
; __device__ __forceinline__ unsigned f2bf(float f) { return pk2(f, f) & 0xffffu; }
; __device__ __forceinline__ void unpack8(const u32x4 u, float* x) { x[0] = bflo(u.x); x[1] = bfhi(u.x); x[2] = bflo(u.y); x[3] = bfhi(u.y); x[4] = bflo(u.z); x[5] = bfhi(u.z); x[6] = bflo(u.w); x[7] = bfhi(u.w); }
; __device__ __forceinline__ int perm16(int e) { return (e & ~12) | ((e >> 1) & 4) | ((e << 1) & 8); }
; __device__ __forceinline__ void delta_rec_stage(LAS unsigned char* buf, int pt, const DeltaPre& dp) {
;     const int tt = pt >> 3, dg = pt & 7, d0 = dg * 16;
;     { LAS bf16* dst = (LAS bf16*)(buf + (pt < 128 ? DR_TI : DR_AT)) + ((pt & 127) >> 2) * 40 + (pt & 3) * 8; *(LAS u32x4*)dst = dp.tia; }
;     if (pt == 0) *(LAS float*)(buf + DR_EGL) = __expf(dp.gl);
;     const float eg = __expf(dp.gct), ekd = __expf(dp.gl - dp.gct);
;     const float fq = dp.nq * eg, fkb = dp.nk * dp.bet * eg, fkd = dp.nk * ekd, bet = dp.bet;
;     float k[16], q[16], v[16];
;     unpack8(dp.k0, k); unpack8(dp.k1, k + 8); unpack8(dp.q0, q); unpack8(dp.q1, q + 8); unpack8(dp.v0, v); unpack8(dp.v1, v + 8);
;     LAS bf16* KB = (LAS bf16*)(buf + DR_KB) + tt * 136 + d0; LAS bf16* QD = (LAS bf16*)(buf + DR_QD) + tt * 136 + d0;
;     *(LAS bf16x8*)KB = pack8(k[0] * fkb, k[1] * fkb, k[2] * fkb, k[3] * fkb, k[8] * fkb, k[9] * fkb, k[10] * fkb, k[11] * fkb);
;     *(LAS bf16x8*)(KB + 8) = pack8(k[4] * fkb, k[5] * fkb, k[6] * fkb, k[7] * fkb, k[12] * fkb, k[13] * fkb, k[14] * fkb, k[15] * fkb);
;     *(LAS bf16x8*)QD = pack8(q[0] * fq, q[1] * fq, q[2] * fq, q[3] * fq, q[8] * fq, q[9] * fq, q[10] * fq, q[11] * fq);
;     *(LAS bf16x8*)(QD + 8) = pack8(q[4] * fq, q[5] * fq, q[6] * fq, q[7] * fq, q[12] * fq, q[13] * fq, q[14] * fq, q[15] * fq);
;     LAS bf16* KDT = (LAS bf16*)(buf + DR_KDT) + d0 * 40 + perm16(tt);
; #pragma unroll
;     for (int e = 0; e < 16; ++e) KDT[e * 40] = (bf16)f2bf(k[e] * fkd);
;     LAS float* VB = (LAS float*)(buf + DR_VB) + tt * 132 + d0;
; #pragma unroll
;     for (int e4 = 0; e4 < 4; ++e4) *(LAS f32x4*)(VB + 4 * e4) = (f32x4){v[4 * e4] * bet, v[4 * e4 + 1] * bet, v[4 * e4 + 2] * bet, v[4 * e4 + 3] * bet};
; }
.LBB0_1840:
	s_or_b64 exec, exec, s[26:27]
	v_mul_f32_e32 v110, 0x3fb8aa3b, v123
	v_exp_f32_e32 v117, v110
	v_sub_f32_e32 v110, v124, v123
	v_mul_f32_e32 v110, 0x3fb8aa3b, v110
	v_exp_f32_e32 v119, v110
	v_mul_f32_e32 v118, v116, v125
	v_mul_f32_e32 v118, v117, v118
	v_lshlrev_b32_e32 v128, 16, v48
	v_and_b32_e32 v129, 0xffff0000, v48
	v_lshlrev_b32_e32 v48, 16, v49
	v_and_b32_e32 v49, 0xffff0000, v49
	v_lshlrev_b32_e32 v130, 16, v44
	v_and_b32_e32 v131, 0xffff0000, v44
	v_lshlrev_b32_e32 v134, 16, v45
	v_and_b32_e32 v135, 0xffff0000, v45
	v_mul_f32_e32 v110, v117, v126
	v_mul_f32_e32 v117, v125, v119
	v_pk_mul_f32 v[124:125], v[118:119], v[128:129] op_sel_hi:[0,1]
	v_pk_mul_f32 v[126:127], v[118:119], v[48:49] op_sel_hi:[0,1]
	v_pk_mul_f32 v[132:133], v[118:119], v[130:131] op_sel_hi:[0,1]
	v_pk_mul_f32 v[44:45], v[118:119], v[134:135] op_sel_hi:[0,1]
	v_add3_u32 v120, s37, v91, v114
	v_cvt_pk_bf16_f32 v124, v124, v125
	v_cvt_pk_bf16_f32 v125, v126, v127
	v_cvt_pk_bf16_f32 v126, v132, v133
	v_cvt_pk_bf16_f32 v127, v44, v45
	ds_write_b128 v120, v[124:127]
	v_lshlrev_b32_e32 v124, 16, v50
	v_and_b32_e32 v125, 0xffff0000, v50
	v_lshlrev_b32_e32 v50, 16, v51
	v_and_b32_e32 v51, 0xffff0000, v51
	v_lshlrev_b32_e32 v132, 16, v46
	v_and_b32_e32 v133, 0xffff0000, v46
	v_lshlrev_b32_e32 v138, 16, v47
	v_and_b32_e32 v139, 0xffff0000, v47
	v_pk_mul_f32 v[44:45], v[118:119], v[124:125] op_sel_hi:[0,1]
	v_pk_mul_f32 v[126:127], v[118:119], v[50:51] op_sel_hi:[0,1]
	v_pk_mul_f32 v[136:137], v[118:119], v[132:133] op_sel_hi:[0,1]
	v_pk_mul_f32 v[118:119], v[118:119], v[138:139] op_sel_hi:[0,1]
	v_cvt_pk_bf16_f32 v44, v44, v45
	v_cvt_pk_bf16_f32 v45, v126, v127
	v_cvt_pk_bf16_f32 v46, v136, v137
	v_cvt_pk_bf16_f32 v47, v118, v119
	ds_write_b128 v120, v[44:47] offset:16
	v_lshlrev_b32_e32 v44, 16, v36
	v_and_b32_e32 v45, 0xffff0000, v36
	v_lshlrev_b32_e32 v36, 16, v37
	v_and_b32_e32 v37, 0xffff0000, v37
	v_lshlrev_b32_e32 v46, 16, v28
	v_and_b32_e32 v47, 0xffff0000, v28
	v_lshlrev_b32_e32 v28, 16, v29
	v_and_b32_e32 v29, 0xffff0000, v29
	v_pk_mul_f32 v[44:45], v[110:111], v[44:45] op_sel_hi:[0,1]
	v_pk_mul_f32 v[36:37], v[110:111], v[36:37] op_sel_hi:[0,1]
	v_pk_mul_f32 v[46:47], v[110:111], v[46:47] op_sel_hi:[0,1]
	v_pk_mul_f32 v[28:29], v[110:111], v[28:29] op_sel_hi:[0,1]
	v_cvt_pk_bf16_f32 v44, v44, v45
	v_cvt_pk_bf16_f32 v45, v36, v37
	v_cvt_pk_bf16_f32 v46, v46, v47
	v_cvt_pk_bf16_f32 v47, v28, v29
	v_lshlrev_b32_e32 v28, 16, v38
	v_and_b32_e32 v29, 0xffff0000, v38
	v_lshlrev_b32_e32 v36, 16, v39
	v_and_b32_e32 v37, 0xffff0000, v39
	v_lshlrev_b32_e32 v38, 16, v30
	v_and_b32_e32 v39, 0xffff0000, v30
	v_lshlrev_b32_e32 v30, 16, v31
	v_and_b32_e32 v31, 0xffff0000, v31
	ds_write_b128 v120, v[44:47] offset:8704
	v_pk_mul_f32 v[28:29], v[110:111], v[28:29] op_sel_hi:[0,1]
	v_pk_mul_f32 v[36:37], v[110:111], v[36:37] op_sel_hi:[0,1]
	v_pk_mul_f32 v[38:39], v[110:111], v[38:39] op_sel_hi:[0,1]
	v_pk_mul_f32 v[44:45], v[110:111], v[30:31] op_sel_hi:[0,1]
	v_cvt_pk_bf16_f32 v28, v28, v29
	v_cvt_pk_bf16_f32 v29, v36, v37
	v_cvt_pk_bf16_f32 v30, v38, v39
	v_cvt_pk_bf16_f32 v31, v44, v45
	ds_write_b128 v120, v[28:31] offset:8720
	v_add3_u32 v28, s37, v90, v80
	v_add3_u32 v28, v28, v81, v82
	v_add_u32_e32 v232, v28, v230
	v_pk_mul_f32 v[190:191], v[116:117], v[128:129] op_sel:[1,0]
	v_pk_mul_f32 v[192:193], v[116:117], v[48:49] op_sel:[1,0]
	v_pk_mul_f32 v[194:195], v[116:117], v[124:125] op_sel:[1,0]
	v_pk_mul_f32 v[196:197], v[116:117], v[50:51] op_sel:[1,0]
	v_pk_mul_f32 v[198:199], v[116:117], v[130:131] op_sel:[1,0]
	v_pk_mul_f32 v[200:201], v[116:117], v[134:135] op_sel:[1,0]
	v_pk_mul_f32 v[202:203], v[116:117], v[132:133] op_sel:[1,0]
	v_pk_mul_f32 v[204:205], v[116:117], v[138:139] op_sel:[1,0]
	v_cvt_pk_bf16_f32 v206, v190, v191
	v_cvt_pk_bf16_f32 v207, v192, v193
	v_cvt_pk_bf16_f32 v208, v194, v195
	v_cvt_pk_bf16_f32 v209, v196, v197
	v_cvt_pk_bf16_f32 v210, v198, v199
	v_cvt_pk_bf16_f32 v211, v200, v201
	v_cvt_pk_bf16_f32 v212, v202, v203
	v_cvt_pk_bf16_f32 v213, v204, v205
	v_mov_b32_dpp v214, v206 row_ror:8 row_mask:0xf bank_mask:0xf
	v_mov_b32_dpp v215, v207 row_ror:8 row_mask:0xf bank_mask:0xf
	v_mov_b32_dpp v216, v208 row_ror:8 row_mask:0xf bank_mask:0xf
	v_mov_b32_dpp v217, v209 row_ror:8 row_mask:0xf bank_mask:0xf
	v_mov_b32_dpp v218, v210 row_ror:8 row_mask:0xf bank_mask:0xf
	v_mov_b32_dpp v219, v211 row_ror:8 row_mask:0xf bank_mask:0xf
	v_mov_b32_dpp v220, v212 row_ror:8 row_mask:0xf bank_mask:0xf
	v_mov_b32_dpp v221, v213 row_ror:8 row_mask:0xf bank_mask:0xf
	v_perm_b32 v190, v214, v206, v231
	v_perm_b32 v191, v215, v207, v231
	v_perm_b32 v192, v216, v208, v231
	v_perm_b32 v193, v217, v209, v231
	v_perm_b32 v194, v218, v210, v231
	v_perm_b32 v195, v219, v211, v231
	v_perm_b32 v196, v220, v212, v231
	v_perm_b32 v197, v221, v213, v231
	ds_write_b32 v232, v190 offset:17408
	ds_write_b32 v232, v191 offset:17568
	ds_write_b32 v232, v192 offset:17728
	ds_write_b32 v232, v193 offset:17888
	ds_write_b32 v232, v194 offset:18048
	ds_write_b32 v232, v195 offset:18208
	ds_write_b32 v232, v196 offset:18368
	ds_write_b32 v232, v197 offset:18528
	v_lshlrev_b32_e32 v28, 16, v16
	v_and_b32_e32 v29, 0xffff0000, v16
	v_lshlrev_b32_e32 v16, 16, v17
	v_and_b32_e32 v17, 0xffff0000, v17
	v_pk_mul_f32 v[30:31], v[116:117], v[16:17] op_sel_hi:[0,1]
	v_lshlrev_b32_e32 v16, 16, v18
	v_and_b32_e32 v17, 0xffff0000, v18
	v_lshlrev_b32_e32 v18, 16, v19
	v_and_b32_e32 v19, 0xffff0000, v19
	v_add3_u32 v110, s37, v88, v111
	v_pk_mul_f32 v[16:17], v[116:117], v[16:17] op_sel_hi:[0,1]
	v_pk_mul_f32 v[18:19], v[116:117], v[18:19] op_sel_hi:[0,1]
	s_and_b32 s26, s15, 32
	ds_write_b128 v110, v[16:19] offset:32784
	v_lshlrev_b32_e32 v16, 16, v12
	v_and_b32_e32 v17, 0xffff0000, v12
	v_lshlrev_b32_e32 v12, 16, v13
	v_and_b32_e32 v13, 0xffff0000, v13
	s_mulk_i32 s26, 0x210
	v_pk_mul_f32 v[16:17], v[116:117], v[16:17] op_sel_hi:[0,1]
	v_pk_mul_f32 v[18:19], v[116:117], v[12:13] op_sel_hi:[0,1]
	v_add_u32_e32 v44, s26, v89
	ds_write_b128 v110, v[16:19] offset:32800
	ds_read_b128 v[16:19], v44
	v_pk_mul_f32 v[28:29], v[116:117], v[28:29] op_sel_hi:[0,1]
	ds_write_b128 v110, v[28:31] offset:32768
	ds_read_b128 v[28:31], v44 offset:16
	ds_read_b128 v[36:39], v44 offset:32
	ds_read_b128 v[44:47], v44 offset:48
	v_lshlrev_b32_e32 v12, 16, v14
	s_waitcnt lgkmcnt(4)
; #define LAS __attribute__((address_space(3)))
; __device__ __forceinline__ float rsq_f(float x) { return __builtin_amdgcn_rsqf(x); }
; __device__ __forceinline__ float red8(float x) { x += dpp_f<0xB1>(x); x += dpp_f<0x4E>(x); x += dpp_f<0x141>(x); return x; }
; __device__ __forceinline__ void unpack8(const u32x4 u, float* x) { x[0] = bflo(u.x); x[1] = bfhi(u.x); x[2] = bflo(u.y); x[3] = bfhi(u.y); x[4] = bflo(u.z); x[5] = bfhi(u.z); x[6] = bflo(u.w); x[7] = bfhi(u.w); }
; #define DR_BAR() do { asm volatile("s_waitcnt lgkmcnt(0)" ::: "memory"); __builtin_amdgcn_s_barrier(); asm volatile("" ::: "memory"); } while (0)
; __device__ __forceinline__ void delta_out_norm(const LAS float* ob, int pt, const float* dn16, const u32x4 z0, const u32x4 z1, bf16* dst) {
;     const LAS float* p = ob + (pt >> 3) * 132 + (pt & 7) * 16;
;     float o[16], z[16];
; #pragma unroll
;     for (int e4 = 0; e4 < 4; ++e4) { const f32x4 t = *(const LAS f32x4*)(p + 4 * e4); o[4 * e4] = t[0]; o[4 * e4 + 1] = t[1]; o[4 * e4 + 2] = t[2]; o[4 * e4 + 3] = t[3]; }
;     float ss = 0.f;
; #pragma unroll
;     for (int e = 0; e < 16; ++e) ss += o[e] * o[e];
;     ss = red8(ss);
;     const float rstd = rsq_f(ss * (1.f / 128.f) + EPS);
;     unpack8(z0, z); unpack8(z1, z + 8);
; #pragma unroll
;     for (int e = 0; e < 16; ++e) o[e] = o[e] * rstd * dn16[e] * z[e];
;     *(bf16x8*)dst = pack8(o[0], o[1], o[2], o[3], o[4], o[5], o[6], o[7]); *(bf16x8*)(dst + 8) = pack8(o[8], o[9], o[10], o[11], o[12], o[13], o[14], o[15]);
; }
; __device__ __forceinline__ void delta_rec_task(const Params& P, LAS unsigned char* lds, int b, int h, int tid) {
;     ...
;         for (int c = 0; c < NC; ++c) {
;             if (c > 0) { dcur = dnxt; zc0 = zn0; zc1 = zn1; }
;             if (c + 2 < NC) delta_pre_load(b, h, c + 2, pt, dnxt);
;             zn0 = *(const u32x4*)(zgp + (size_t)c * 32 * D); zn1 = *(const u32x4*)(zgp + (size_t)c * 32 * D + 8);
;             if (c + 1 < NC) delta_rec_stage(lds + ((c + 1) & 1) * DR_BUF, pt, dcur);
;             if (c > 0) delta_out_norm((const LAS float*)(lds + DR_OB) + ((c - 1) & 1) * 32 * 132, pt, dn16, zc0, zc1, zgp + (size_t)(c - 1) * 32 * D);
;             DR_BAR();
;         }
	v_mul_f32_e32 v50, v17, v17
	v_fmac_f32_e32 v50, v16, v16
	v_fmac_f32_e32 v50, v18, v18
	v_fmac_f32_e32 v50, v19, v19
	s_waitcnt lgkmcnt(2)
	v_fmac_f32_e32 v50, v28, v28
	v_fmac_f32_e32 v50, v29, v29
	v_fmac_f32_e32 v50, v30, v30
	v_fmac_f32_e32 v50, v31, v31
	s_waitcnt lgkmcnt(1)
	v_fmac_f32_e32 v50, v36, v36
	v_fmac_f32_e32 v50, v37, v37
	v_pk_mul_f32 v[48:49], v[38:39], v[38:39]
	v_and_b32_e32 v13, 0xffff0000, v14
	v_lshlrev_b32_e32 v14, 16, v15
	v_and_b32_e32 v15, 0xffff0000, v15
	v_add_f32_e32 v48, v48, v50
	v_pk_mul_f32 v[12:13], v[116:117], v[12:13] op_sel_hi:[0,1]
	v_pk_mul_f32 v[14:15], v[116:117], v[14:15] op_sel_hi:[0,1]
	v_add_f32_e32 v116, v49, v48
	s_waitcnt lgkmcnt(0)
	v_pk_mul_f32 v[50:51], v[44:45], v[44:45]
	v_pk_mul_f32 v[48:49], v[46:47], v[46:47]
	v_add_f32_e32 v50, v50, v116
	v_add_f32_e32 v50, v51, v50
	v_add_f32_e32 v48, v48, v50
	v_add_f32_e32 v48, v49, v48
	ds_write_b128 v110, v[12:15] offset:32816
	v_lshlrev_b32_e32 v12, 16, v8
	v_add_f32_dpp v48, v48, v48 quad_perm:[1,0,3,2] row_mask:0xf bank_mask:0xf bound_ctrl:1
	v_and_b32_e32 v13, 0xffff0000, v8
	v_lshlrev_b32_e32 v8, 16, v9
	v_add_f32_dpp v48, v48, v48 quad_perm:[2,3,0,1] row_mask:0xf bank_mask:0xf bound_ctrl:1
	v_and_b32_e32 v9, 0xffff0000, v9
	s_add_i32 s36, s36, 1
	v_add_f32_dpp v48, v48, v48 row_half_mirror row_mask:0xf bank_mask:0xf bound_ctrl:1
	v_fmamk_f32 v48, v48, 0x3c000000, v83
	v_rsq_f32_e32 v48, v48
	s_add_u32 s12, s12, 0x10000
	s_addc_u32 s13, s13, 0
	s_add_u32 s4, s4, 0x80
	v_pk_mul_f32 v[14:15], v[16:17], v[48:49] op_sel_hi:[1,0]
	v_pk_mul_f32 v[16:17], v[28:29], v[48:49] op_sel_hi:[1,0]
	v_pk_mul_f32 v[14:15], v[102:103], v[14:15]
	v_pk_mul_f32 v[16:17], v[98:99], v[16:17]
	v_pk_mul_f32 v[12:13], v[14:15], v[12:13]
	v_pk_mul_f32 v[14:15], v[18:19], v[48:49] op_sel_hi:[1,0]
	v_pk_mul_f32 v[18:19], v[36:37], v[48:49] op_sel_hi:[1,0]
	v_pk_mul_f32 v[14:15], v[100:101], v[14:15]
	v_pk_mul_f32 v[18:19], v[94:95], v[18:19]
	v_pk_mul_f32 v[8:9], v[14:15], v[8:9]
	v_lshlrev_b32_e32 v14, 16, v10
	v_and_b32_e32 v15, 0xffff0000, v10
	v_pk_mul_f32 v[14:15], v[16:17], v[14:15]
	v_pk_mul_f32 v[16:17], v[30:31], v[48:49] op_sel_hi:[1,0]
	v_lshlrev_b32_e32 v10, 16, v11
	v_and_b32_e32 v11, 0xffff0000, v11
	v_pk_mul_f32 v[16:17], v[96:97], v[16:17]
	v_pk_mul_f32 v[28:29], v[44:45], v[48:49] op_sel_hi:[1,0]
	v_pk_mul_f32 v[10:11], v[16:17], v[10:11]
	v_lshlrev_b32_e32 v16, 16, v4
	v_and_b32_e32 v17, 0xffff0000, v4
	v_pk_mul_f32 v[16:17], v[18:19], v[16:17]
	v_pk_mul_f32 v[18:19], v[38:39], v[48:49] op_sel_hi:[1,0]
	v_lshlrev_b32_e32 v4, 16, v5
	v_and_b32_e32 v5, 0xffff0000, v5
	v_pk_mul_f32 v[18:19], v[92:93], v[18:19]
	v_pk_mul_f32 v[28:29], v[104:105], v[28:29]
	v_pk_mul_f32 v[18:19], v[18:19], v[4:5]
	v_lshlrev_b32_e32 v4, 16, v6
	v_and_b32_e32 v5, 0xffff0000, v6
	v_pk_mul_f32 v[28:29], v[28:29], v[4:5]
	v_lshlrev_b32_e32 v4, 16, v7
	v_and_b32_e32 v5, 0xffff0000, v7
	v_pk_mul_f32 v[6:7], v[46:47], v[48:49] op_sel_hi:[1,0]
	s_addc_u32 s5, s5, 0
	v_pk_mul_f32 v[6:7], v[106:107], v[6:7]
	s_add_i32 s15, s15, 32
	v_pk_mul_f32 v[30:31], v[6:7], v[4:5]
	v_cvt_pk_bf16_f32 v5, v8, v9
	v_add_co_u32_e32 v8, vcc, s31, v78
	v_cvt_pk_bf16_f32 v4, v12, v13
	v_cvt_pk_bf16_f32 v6, v14, v15
	v_cvt_pk_bf16_f32 v7, v10, v11
	v_addc_co_u32_e32 v9, vcc, 0, v79, vcc
	global_store_dwordx4 v[8:9], v[4:7], off
	s_cmp_eq_u32 s12, 0x3d0000
	v_lshl_add_u64 v[70:71], v[70:71], 0, s[24:25]
	v_cvt_pk_bf16_f32 v4, v16, v17
	v_cvt_pk_bf16_f32 v5, v18, v19
	v_cvt_pk_bf16_f32 v6, v28, v29
	v_cvt_pk_bf16_f32 v7, v30, v31
	global_store_dwordx4 v[8:9], v[4:7], off offset:16
	s_waitcnt lgkmcnt(0)
	s_barrier
	s_cbranch_scc1 .LBB0_1842
	s_waitcnt vmcnt(3)
	v_mov_b64_e32 v[8:9], v[24:25]
	s_waitcnt vmcnt(2)
	v_mov_b64_e32 v[4:5], v[20:21]
	v_mov_b64_e32 v[48:49], v[64:65]
	v_mov_b64_e32 v[44:45], v[60:61]
	v_mov_b64_e32 v[36:37], v[56:57]
	v_mov_b64_e32 v[28:29], v[52:53]
	v_mov_b64_e32 v[16:17], v[40:41]
	v_mov_b64_e32 v[12:13], v[32:33]
	v_mov_b64_e32 v[10:11], v[26:27]
	v_mov_b64_e32 v[6:7], v[22:23]
	v_mov_b64_e32 v[50:51], v[66:67]
	v_mov_b64_e32 v[46:47], v[62:63]
	v_mov_b64_e32 v[38:39], v[58:59]
	v_mov_b64_e32 v[30:31], v[54:55]
	v_mov_b64_e32 v[18:19], v[42:43]
	v_mov_b64_e32 v[14:15], v[34:35]
	v_mov_b32_e32 v123, v84
	v_mov_b32_e32 v124, v85
	v_mov_b32_e32 v116, v68
	v_mov_b32_e32 v125, v86
	v_mov_b32_e32 v126, v87
	s_branch .LBB0_1838
